# code placement: fused lean tile and everything behind it shifted by 4 bytes (one s_nop before the block)
# speedup vs baseline: 1.0001x; 1.0001x over previous
.LBB0_658:
	s_and_b64 vcc, exec, s[0:1]
	s_cbranch_vccz .LBB0_653
	s_lshl_b32 s0, s76, 14
	s_or_b32 s76, s0, s21
	s_lshl_b32 s77, s77, 6
	s_add_i32 s78, s77, 63
	s_cmp_gt_i32 s78, s72
	s_cbranch_scc1 .Lflt_no
	s_cmp_lt_i32 s77, s71
	s_cbranch_scc1 .Lflt_no
	s_sub_i32 s0, s33, s78
	s_cmpk_gt_i32 s0, 0x7f
	s_cselect_b64 s[0:1], -1, 0
	s_or_b64 s[0:1], s[0:1], s[30:31]
	s_and_b64 vcc, exec, s[0:1]
	s_cbranch_vccz .Lflt_no
	s_nop 0
	v_add_u32_e32 v3, s76, v198
	ds_read_b128 v[4:7], v3
	v_add_u32_e32 v16, s76, v206
	ds_read_b128 v[8:11], v16
	v_add_u32_e32 v17, s76, v207
	ds_read_b128 v[12:15], v17
	v_add_u32_e32 v238, s76, v208
	ds_read_b128 v[214:217], v238
	ds_read_b128 v[234:237], v3 offset:4096
	ds_read_b128 v[244:247], v16 offset:4096
	ds_read_b128 v[248:251], v17 offset:4096
	ds_read_b128 v[252:255], v238 offset:4096
	s_setprio 1
	s_waitcnt lgkmcnt(7)
	v_mfma_f32_32x32x16_bf16 v[118:133], v[4:7], v[134:137], v[86:101]
	s_waitcnt lgkmcnt(6)
	v_mfma_f32_32x32x16_bf16 v[118:133], v[8:11], v[138:141], v[118:133]
	s_waitcnt lgkmcnt(5)
	v_mfma_f32_32x32x16_bf16 v[118:133], v[12:15], v[142:145], v[118:133]
	s_waitcnt lgkmcnt(4)
	v_mfma_f32_32x32x16_bf16 v[118:133], v[214:217], v[150:153], v[118:133]
	s_add_i32 s0, s76, 0x2000
	v_mfma_f32_32x32x16_bf16 v[102:117], v[4:7], v[146:149], v[86:101]
	v_add_u32_e32 v3, s0, v200
	ds_read_b64_tr_b16 v[4:5], v3 offset:0
	ds_read_b64_tr_b16 v[6:7], v3 offset:1024
	v_mfma_f32_32x32x16_bf16 v[102:117], v[8:11], v[154:157], v[102:117]
	ds_read_b64_tr_b16 v[8:9], v3 offset:2048
	ds_read_b64_tr_b16 v[10:11], v3 offset:3072
	s_nop 4
	v_exp_f32_e32 v118, v118
	v_exp_f32_e32 v119, v119
	v_exp_f32_e32 v120, v120
	v_mfma_f32_32x32x16_bf16 v[102:117], v[12:15], v[158:161], v[102:117]
	v_add_u32_e32 v3, s0, v201
	ds_read_b64_tr_b16 v[12:13], v3 offset:0
	ds_read_b64_tr_b16 v[14:15], v3 offset:1024
	v_exp_f32_e32 v121, v121
	v_exp_f32_e32 v122, v122
	v_exp_f32_e32 v123, v123
	v_mfma_f32_32x32x16_bf16 v[102:117], v[214:217], v[162:165], v[102:117]
	ds_read_b64_tr_b16 v[214:215], v3 offset:2048
	ds_read_b64_tr_b16 v[216:217], v3 offset:3072
	v_exp_f32_e32 v124, v124
	v_exp_f32_e32 v125, v125
	v_exp_f32_e32 v126, v126
	s_waitcnt lgkmcnt(8)
	v_mfma_f32_32x32x16_bf16 v[218:233], v[234:237], v[134:137], v[86:101]
	v_exp_f32_e32 v127, v127
	v_exp_f32_e32 v128, v128
	v_exp_f32_e32 v129, v129
	v_mfma_f32_32x32x16_bf16 v[218:233], v[244:247], v[138:141], v[218:233]
	v_exp_f32_e32 v130, v130
	v_exp_f32_e32 v131, v131
	v_exp_f32_e32 v132, v132
	v_mfma_f32_32x32x16_bf16 v[218:233], v[248:251], v[142:145], v[218:233]
	v_exp_f32_e32 v133, v133
	v_add_f32_e32 v16, v118, v120
	v_add_f32_e32 v17, v119, v121
	v_add_f32_e32 v16, v16, v122
	v_add_f32_e32 v17, v17, v123
	v_add_f32_e32 v16, v16, v124
	v_add_f32_e32 v17, v17, v125
	v_cvt_pk_bf16_f32 v118, v118, v119
	v_cvt_pk_bf16_f32 v119, v120, v121
	v_cvt_pk_bf16_f32 v120, v122, v123
	v_mfma_f32_32x32x16_bf16 v[218:233], v[252:255], v[150:153], v[218:233]
	v_cvt_pk_bf16_f32 v121, v124, v125
	v_cvt_pk_bf16_f32 v122, v126, v127
	v_cvt_pk_bf16_f32 v123, v128, v129
	v_cvt_pk_bf16_f32 v124, v130, v131
	v_cvt_pk_bf16_f32 v125, v132, v133
	v_add_f32_e32 v16, v16, v126
	v_add_f32_e32 v17, v17, v127
	v_add_f32_e32 v16, v16, v128
	v_add_f32_e32 v17, v17, v129
	v_add_f32_e32 v16, v16, v130
	v_add_f32_e32 v17, v17, v131
	v_add_f32_e32 v16, v16, v132
	v_add_f32_e32 v17, v17, v133
	s_waitcnt lgkmcnt(0)
	v_mfma_f32_32x32x16_bf16 v[20:35], v[4:7], v[118:121], v[20:35]
	v_exp_f32_e32 v102, v102
	v_exp_f32_e32 v103, v103
	v_exp_f32_e32 v104, v104
	v_mfma_f32_32x32x16_bf16 v[36:51], v[12:15], v[118:121], v[36:51]
	v_exp_f32_e32 v105, v105
	v_exp_f32_e32 v106, v106
	v_exp_f32_e32 v107, v107
	v_mfma_f32_32x32x16_bf16 v[20:35], v[8:11], v[122:125], v[20:35]
	v_exp_f32_e32 v108, v108
	v_exp_f32_e32 v109, v109
	v_exp_f32_e32 v110, v110
	v_mfma_f32_32x32x16_bf16 v[36:51], v[214:217], v[122:125], v[36:51]
	v_exp_f32_e32 v111, v111
	v_exp_f32_e32 v112, v112
	v_exp_f32_e32 v113, v113
	s_add_i32 s0, s76, 0x3000
	v_mfma_f32_32x32x16_bf16 v[118:133], v[234:237], v[146:149], v[86:101]
	v_add_u32_e32 v3, s0, v200
	ds_read_b64_tr_b16 v[234:235], v3 offset:0
	ds_read_b64_tr_b16 v[236:237], v3 offset:1024
	v_exp_f32_e32 v114, v114
	v_exp_f32_e32 v115, v115
	v_exp_f32_e32 v116, v116
	v_mfma_f32_32x32x16_bf16 v[118:133], v[244:247], v[154:157], v[118:133]
	ds_read_b64_tr_b16 v[244:245], v3 offset:2048
	ds_read_b64_tr_b16 v[246:247], v3 offset:3072
	v_exp_f32_e32 v117, v117
	v_add_f32_e32 v238, v102, v104
	v_add_f32_e32 v239, v103, v105
	v_add_f32_e32 v238, v238, v106
	v_add_f32_e32 v239, v239, v107
	v_add_f32_e32 v238, v238, v108
	v_add_f32_e32 v239, v239, v109
	v_cvt_pk_bf16_f32 v102, v102, v103
	v_cvt_pk_bf16_f32 v103, v104, v105
	v_mfma_f32_32x32x16_bf16 v[118:133], v[248:251], v[158:161], v[118:133]
	v_add_u32_e32 v3, s0, v201
	ds_read_b64_tr_b16 v[248:249], v3 offset:0
	ds_read_b64_tr_b16 v[250:251], v3 offset:1024
	v_cvt_pk_bf16_f32 v104, v106, v107
	v_cvt_pk_bf16_f32 v105, v108, v109
	v_cvt_pk_bf16_f32 v106, v110, v111
	v_cvt_pk_bf16_f32 v107, v112, v113
	v_cvt_pk_bf16_f32 v108, v114, v115
	v_cvt_pk_bf16_f32 v109, v116, v117
	v_mfma_f32_32x32x16_bf16 v[118:133], v[252:255], v[162:165], v[118:133]
	ds_read_b64_tr_b16 v[252:253], v3 offset:2048
	ds_read_b64_tr_b16 v[254:255], v3 offset:3072
	v_add_f32_e32 v238, v238, v110
	v_add_f32_e32 v239, v239, v111
	v_add_f32_e32 v238, v238, v112
	v_add_f32_e32 v239, v239, v113
	v_add_f32_e32 v238, v238, v114
	v_add_f32_e32 v239, v239, v115
	v_add_f32_e32 v238, v238, v116
	v_add_f32_e32 v239, v239, v117
	v_mfma_f32_32x32x16_bf16 v[68:83], v[4:7], v[102:105], v[68:83]
	v_exp_f32_e32 v218, v218
	v_exp_f32_e32 v219, v219
	v_exp_f32_e32 v220, v220
	v_mfma_f32_32x32x16_bf16 v[52:67], v[12:15], v[102:105], v[52:67]
	v_exp_f32_e32 v221, v221
	v_exp_f32_e32 v222, v222
	v_exp_f32_e32 v223, v223
	v_mfma_f32_32x32x16_bf16 v[68:83], v[8:11], v[106:109], v[68:83]
	v_exp_f32_e32 v224, v224
	v_exp_f32_e32 v225, v225
	v_exp_f32_e32 v226, v226
	v_mfma_f32_32x32x16_bf16 v[52:67], v[214:217], v[106:109], v[52:67]
	v_exp_f32_e32 v227, v227
	v_exp_f32_e32 v228, v228
	v_exp_f32_e32 v229, v229
	v_exp_f32_e32 v230, v230
	v_exp_f32_e32 v231, v231
	v_exp_f32_e32 v232, v232
	v_exp_f32_e32 v233, v233
	v_add_f32_e32 v16, v16, v218
	v_add_f32_e32 v17, v17, v219
	v_add_f32_e32 v16, v16, v220
	v_add_f32_e32 v17, v17, v221
	v_add_f32_e32 v16, v16, v222
	v_add_f32_e32 v17, v17, v223
	v_add_f32_e32 v16, v16, v224
	v_add_f32_e32 v17, v17, v225
	v_cvt_pk_bf16_f32 v218, v218, v219
	v_cvt_pk_bf16_f32 v219, v220, v221
	v_cvt_pk_bf16_f32 v220, v222, v223
	v_cvt_pk_bf16_f32 v221, v224, v225
	v_cvt_pk_bf16_f32 v222, v226, v227
	v_cvt_pk_bf16_f32 v223, v228, v229
	v_cvt_pk_bf16_f32 v224, v230, v231
	v_cvt_pk_bf16_f32 v225, v232, v233
	s_waitcnt lgkmcnt(0)
	v_mfma_f32_32x32x16_bf16 v[20:35], v[234:237], v[218:221], v[20:35]
	v_exp_f32_e32 v118, v118
	v_exp_f32_e32 v119, v119
	v_exp_f32_e32 v120, v120
	v_mfma_f32_32x32x16_bf16 v[36:51], v[248:251], v[218:221], v[36:51]
	v_exp_f32_e32 v121, v121
	v_exp_f32_e32 v122, v122
	v_exp_f32_e32 v123, v123
	v_mfma_f32_32x32x16_bf16 v[20:35], v[244:247], v[222:225], v[20:35]
	v_exp_f32_e32 v124, v124
	v_exp_f32_e32 v125, v125
	v_exp_f32_e32 v126, v126
	v_mfma_f32_32x32x16_bf16 v[36:51], v[252:255], v[222:225], v[36:51]
	v_exp_f32_e32 v127, v127
	v_exp_f32_e32 v128, v128
	v_exp_f32_e32 v129, v129
	v_exp_f32_e32 v130, v130
	v_exp_f32_e32 v131, v131
	v_exp_f32_e32 v132, v132
	v_exp_f32_e32 v133, v133
	v_add_f32_e32 v238, v238, v118
	v_add_f32_e32 v239, v239, v119
	v_add_f32_e32 v238, v238, v120
	v_add_f32_e32 v239, v239, v121
	v_add_f32_e32 v238, v238, v122
	v_add_f32_e32 v239, v239, v123
	v_add_f32_e32 v238, v238, v124
	v_add_f32_e32 v239, v239, v125
	v_cvt_pk_bf16_f32 v118, v118, v119
	v_cvt_pk_bf16_f32 v119, v120, v121
	v_cvt_pk_bf16_f32 v120, v122, v123
	v_cvt_pk_bf16_f32 v121, v124, v125
	v_cvt_pk_bf16_f32 v122, v126, v127
	v_cvt_pk_bf16_f32 v123, v128, v129
	v_cvt_pk_bf16_f32 v124, v130, v131
	v_cvt_pk_bf16_f32 v125, v132, v133
	v_mfma_f32_32x32x16_bf16 v[68:83], v[234:237], v[118:121], v[68:83]
	v_add_f32_e32 v16, v16, v226
	v_add_f32_e32 v17, v17, v227
	v_add_f32_e32 v16, v16, v228
	v_add_f32_e32 v17, v17, v229
	v_mfma_f32_32x32x16_bf16 v[52:67], v[248:251], v[118:121], v[52:67]
	v_add_f32_e32 v16, v16, v230
	v_add_f32_e32 v17, v17, v231
	v_add_f32_e32 v16, v16, v232
	v_add_f32_e32 v17, v17, v233
	v_mfma_f32_32x32x16_bf16 v[68:83], v[244:247], v[122:125], v[68:83]
	v_add_f32_e32 v238, v238, v126
	v_add_f32_e32 v239, v239, v127
	v_add_f32_e32 v238, v238, v128
	v_add_f32_e32 v239, v239, v129
	v_mfma_f32_32x32x16_bf16 v[52:67], v[252:255], v[122:125], v[52:67]
	v_add_f32_e32 v238, v238, v130
	v_add_f32_e32 v239, v239, v131
	v_add_f32_e32 v238, v238, v132
	v_add_f32_e32 v239, v239, v133
	s_setprio 0
	v_add_f32_e32 v16, v16, v17
	v_add_f32_e32 v238, v238, v239
	v_add_f32_e32 v180, v180, v16
	v_add_f32_e32 v181, v181, v238
	s_branch .LBB0_653
